# ret_out: static s_setprio 1 for waves 0-3 (the other half; A/B of the per-half priority raise)
# speedup vs baseline: 1.0026x; 1.0024x over previous
.Lp6_retout_entry:
	v_readfirstlane_b32 s99, v160
	s_nop 3
	s_lshr_b32 s99, s99, 8
	s_cmp_eq_u32 s99, 0
	s_cbranch_scc0 .Lro_prio_done
	s_setprio 1
